# cross-attention sample units: all 32 query-slab loads issued up front as prefetch before the serial load-add chain
# baseline (speedup 1.0000x reference)
.LBB0_1272:
	s_mov_b64 s[12:13], s[0:1]
	s_load_dwordx2 s[48:49], s[12:13], 0x10
	s_and_b32 s12, s11, -4
	s_and_b32 s68, s33, 0x180
	s_ashr_i32 s13, s12, 31
	s_lshl_b32 s14, s68, 2
	v_lshl_add_u64 v[2:3], v[36:37], 0, s[14:15]
	s_lshl_b64 vcc, s[12:13], 11
	s_mov_b64 s[46:47], s[0:1]
	v_lshl_add_u64 v[16:17], v[2:3], 0, vcc
	global_load_dwordx4 v[2:5], v[16:17], off offset:2048
	s_mov_b32 vcc_lo, 0x1000
	s_mov_b32 vcc_hi, 0
	s_nop 0
	v_lshl_add_u64 v[18:19], v[16:17], 0, vcc
	global_load_dwordx4 v[2:5], v[18:19], off
	global_load_dwordx4 v[2:5], v[18:19], off offset:2048
	s_mov_b32 vcc_lo, 0x40000
	s_mov_b32 vcc_hi, 0
	s_nop 0
	v_lshl_add_u64 v[18:19], v[16:17], 0, vcc
	global_load_dwordx4 v[2:5], v[18:19], off
	global_load_dwordx4 v[2:5], v[18:19], off offset:2048
	s_mov_b32 vcc_lo, 0x41000
	s_mov_b32 vcc_hi, 0
	s_nop 0
	v_lshl_add_u64 v[18:19], v[16:17], 0, vcc
	global_load_dwordx4 v[2:5], v[18:19], off
	global_load_dwordx4 v[2:5], v[18:19], off offset:2048
	s_mov_b32 vcc_lo, 0x80000
	s_mov_b32 vcc_hi, 0
	s_nop 0
	v_lshl_add_u64 v[18:19], v[16:17], 0, vcc
	global_load_dwordx4 v[2:5], v[18:19], off
	global_load_dwordx4 v[2:5], v[18:19], off offset:2048
	s_mov_b32 vcc_lo, 0x81000
	s_mov_b32 vcc_hi, 0
	s_nop 0
	v_lshl_add_u64 v[18:19], v[16:17], 0, vcc
	global_load_dwordx4 v[2:5], v[18:19], off
	global_load_dwordx4 v[2:5], v[18:19], off offset:2048
	s_mov_b32 vcc_lo, 0xc0000
	s_mov_b32 vcc_hi, 0
	s_nop 0
	v_lshl_add_u64 v[18:19], v[16:17], 0, vcc
	global_load_dwordx4 v[2:5], v[18:19], off
	global_load_dwordx4 v[2:5], v[18:19], off offset:2048
	s_mov_b32 vcc_lo, 0xc1000
	s_mov_b32 vcc_hi, 0
	s_nop 0
	v_lshl_add_u64 v[18:19], v[16:17], 0, vcc
	global_load_dwordx4 v[2:5], v[18:19], off
	global_load_dwordx4 v[2:5], v[18:19], off offset:2048
	s_mov_b32 vcc_lo, 0x100000
	s_mov_b32 vcc_hi, 0
	s_nop 0
	v_lshl_add_u64 v[18:19], v[16:17], 0, vcc
	global_load_dwordx4 v[2:5], v[18:19], off
	global_load_dwordx4 v[2:5], v[18:19], off offset:2048
	s_mov_b32 vcc_lo, 0x101000
	s_mov_b32 vcc_hi, 0
	s_nop 0
	v_lshl_add_u64 v[18:19], v[16:17], 0, vcc
	global_load_dwordx4 v[2:5], v[18:19], off
	global_load_dwordx4 v[2:5], v[18:19], off offset:2048
	s_mov_b32 vcc_lo, 0x140000
	s_mov_b32 vcc_hi, 0
	s_nop 0
	v_lshl_add_u64 v[18:19], v[16:17], 0, vcc
	global_load_dwordx4 v[2:5], v[18:19], off
	global_load_dwordx4 v[2:5], v[18:19], off offset:2048
	s_mov_b32 vcc_lo, 0x141000
	s_mov_b32 vcc_hi, 0
	s_nop 0
	v_lshl_add_u64 v[18:19], v[16:17], 0, vcc
	global_load_dwordx4 v[2:5], v[18:19], off
	global_load_dwordx4 v[2:5], v[18:19], off offset:2048
	s_mov_b32 vcc_lo, 0x180000
	s_mov_b32 vcc_hi, 0
	s_nop 0
	v_lshl_add_u64 v[18:19], v[16:17], 0, vcc
	global_load_dwordx4 v[2:5], v[18:19], off
	global_load_dwordx4 v[2:5], v[18:19], off offset:2048
	s_mov_b32 vcc_lo, 0x181000
	s_mov_b32 vcc_hi, 0
	s_nop 0
	v_lshl_add_u64 v[18:19], v[16:17], 0, vcc
	global_load_dwordx4 v[2:5], v[18:19], off
	global_load_dwordx4 v[2:5], v[18:19], off offset:2048
	s_mov_b32 vcc_lo, 0x1c0000
	s_mov_b32 vcc_hi, 0
	s_nop 0
	v_lshl_add_u64 v[18:19], v[16:17], 0, vcc
	global_load_dwordx4 v[2:5], v[18:19], off
	global_load_dwordx4 v[2:5], v[18:19], off offset:2048
	s_mov_b32 vcc_lo, 0x1c1000
	s_mov_b32 vcc_hi, 0
	s_nop 0
	v_lshl_add_u64 v[18:19], v[16:17], 0, vcc
	global_load_dwordx4 v[2:5], v[18:19], off
	global_load_dwordx4 v[2:5], v[18:19], off offset:2048
	global_load_dwordx4 v[2:5], v[16:17], off
	s_mov_b32 s13, 0x40000
	v_add_co_u32_e32 v18, vcc, s13, v16
	s_mov_b32 s13, 0x41000
	s_nop 0
	v_addc_co_u32_e32 v19, vcc, 0, v17, vcc
	s_ashr_i32 s50, s11, 2
	s_ashr_i32 s51, s50, 31
	s_lshl_b64 s[50:51], s[50:51], 17
	s_or_b32 s50, s50, s68
	s_lshl_b64 s[50:51], s[50:51], 2
	s_waitcnt lgkmcnt(0)
	s_add_u32 s48, s48, s50
	s_addc_u32 s49, s49, s51
	v_lshl_add_u64 v[90:91], s[48:49], 0, v[70:71]
	s_waitcnt vmcnt(0)
	v_pk_add_f32 v[10:11], v[2:3], 0 op_sel_hi:[1,0]
	v_add_co_u32_e32 v2, vcc, s13, v16
	v_pk_add_f32 v[8:9], v[4:5], 0 op_sel_hi:[1,0]
	s_nop 0
	v_addc_co_u32_e32 v3, vcc, 0, v17, vcc
	global_load_dwordx4 v[4:7], v[2:3], off offset:-4096
	s_mov_b32 s13, 0x80000
	v_add_co_u32_e32 v24, vcc, s13, v16
	s_mov_b32 s13, 0x81000
	s_nop 0
	v_addc_co_u32_e32 v25, vcc, 0, v17, vcc
	s_waitcnt vmcnt(0)
	v_pk_add_f32 v[12:13], v[8:9], v[6:7]
	v_add_co_u32_e32 v8, vcc, s13, v16
	v_pk_add_f32 v[10:11], v[10:11], v[4:5]
	s_nop 0
	v_addc_co_u32_e32 v9, vcc, 0, v17, vcc
	global_load_dwordx4 v[4:7], v[8:9], off offset:-4096
	s_mov_b32 s13, 0xc0000
	v_add_co_u32_e32 v26, vcc, s13, v16
	s_mov_b32 s13, 0xc1000
	s_nop 0
	v_addc_co_u32_e32 v27, vcc, 0, v17, vcc
	s_waitcnt vmcnt(0)
	v_pk_add_f32 v[14:15], v[12:13], v[6:7]
	v_add_co_u32_e32 v12, vcc, s13, v16
	v_pk_add_f32 v[10:11], v[10:11], v[4:5]
	s_nop 0
	v_addc_co_u32_e32 v13, vcc, 0, v17, vcc
	global_load_dwordx4 v[4:7], v[12:13], off offset:-4096
	s_mov_b32 s13, 0x100000
	v_add_co_u32_e32 v28, vcc, s13, v16
	s_mov_b32 s13, 0x101000
	s_nop 0
	v_addc_co_u32_e32 v29, vcc, 0, v17, vcc
	s_waitcnt vmcnt(0)
	v_pk_add_f32 v[20:21], v[14:15], v[6:7]
	v_add_co_u32_e32 v14, vcc, s13, v16
	v_pk_add_f32 v[10:11], v[10:11], v[4:5]
	s_nop 0
	v_addc_co_u32_e32 v15, vcc, 0, v17, vcc
	global_load_dwordx4 v[4:7], v[14:15], off offset:-4096
	s_mov_b32 s13, 0x140000
	v_add_co_u32_e32 v30, vcc, s13, v16
	s_mov_b32 s13, 0x141000
	s_nop 0
	v_addc_co_u32_e32 v31, vcc, 0, v17, vcc
	s_waitcnt vmcnt(0)
	v_pk_add_f32 v[10:11], v[10:11], v[4:5]
	v_add_co_u32_e32 v4, vcc, s13, v16
	v_pk_add_f32 v[6:7], v[20:21], v[6:7]
	s_nop 0
	v_addc_co_u32_e32 v5, vcc, 0, v17, vcc
	global_load_dwordx4 v[20:23], v[4:5], off offset:-4096
	s_mov_b32 s13, 0x180000
	v_add_co_u32_e32 v78, vcc, s13, v16
	s_mov_b32 s13, 0x181000
	s_nop 0
	v_addc_co_u32_e32 v79, vcc, 0, v17, vcc
	s_waitcnt vmcnt(0)
	v_pk_add_f32 v[32:33], v[6:7], v[22:23]
	v_add_co_u32_e32 v6, vcc, s13, v16
	v_pk_add_f32 v[10:11], v[10:11], v[20:21]
	s_nop 0
	v_addc_co_u32_e32 v7, vcc, 0, v17, vcc
	global_load_dwordx4 v[20:23], v[6:7], off offset:-4096
	s_mov_b32 s13, 0x1c0000
	v_add_co_u32_e32 v80, vcc, s13, v16
	s_mov_b32 s13, 0x1c1000
	s_nop 0
	v_addc_co_u32_e32 v81, vcc, 0, v17, vcc
	s_waitcnt vmcnt(0)
	v_pk_add_f32 v[74:75], v[10:11], v[20:21]
	v_add_co_u32_e32 v10, vcc, s13, v16
	v_pk_add_f32 v[32:33], v[32:33], v[22:23]
	s_nop 0
	v_addc_co_u32_e32 v11, vcc, 0, v17, vcc
	global_load_dwordx4 v[20:23], v[10:11], off offset:-4096
	s_movk_i32 s13, 0x1000
	s_waitcnt vmcnt(0)
	v_pk_add_f32 v[20:21], v[74:75], v[20:21]
	v_pk_add_f32 v[22:23], v[32:33], v[22:23]
	v_cvt_pk_bf16_f32 v20, v20, v21
	v_cvt_pk_bf16_f32 v73, v22, v23
	v_lshlrev_b32_e32 v76, 16, v20
	v_and_b32_e32 v74, 0xffff0000, v20
	global_load_dwordx4 v[20:23], v[16:17], off offset:2048
	v_lshlrev_b32_e32 v88, 16, v73
	v_and_b32_e32 v86, 0xffff0000, v73
	s_waitcnt vmcnt(0)
	v_pk_add_f32 v[32:33], v[20:21], 0 op_sel_hi:[1,0]
	global_load_dwordx4 v[18:21], v[18:19], off offset:2048
	v_pk_add_f32 v[22:23], v[22:23], 0 op_sel_hi:[1,0]
	s_waitcnt vmcnt(0)
	v_pk_add_f32 v[32:33], v[32:33], v[18:19]
	v_pk_add_f32 v[22:23], v[22:23], v[20:21]
	global_load_dwordx4 v[18:21], v[24:25], off offset:2048
	s_waitcnt vmcnt(0)
	v_pk_add_f32 v[22:23], v[22:23], v[20:21]
	v_pk_add_f32 v[24:25], v[32:33], v[18:19]
	global_load_dwordx4 v[18:21], v[26:27], off offset:2048
	s_waitcnt vmcnt(0)
	v_pk_add_f32 v[22:23], v[22:23], v[20:21]
	v_pk_add_f32 v[24:25], v[24:25], v[18:19]
	global_load_dwordx4 v[18:21], v[28:29], off offset:2048
	s_waitcnt vmcnt(0)
	v_pk_add_f32 v[22:23], v[22:23], v[20:21]
	v_pk_add_f32 v[24:25], v[24:25], v[18:19]
	global_load_dwordx4 v[18:21], v[30:31], off offset:2048
	s_waitcnt vmcnt(0)
	v_pk_add_f32 v[22:23], v[22:23], v[20:21]
	v_pk_add_f32 v[24:25], v[24:25], v[18:19]
	global_load_dwordx4 v[18:21], v[78:79], off offset:2048
	s_waitcnt vmcnt(0)
	v_pk_add_f32 v[22:23], v[22:23], v[20:21]
	v_pk_add_f32 v[24:25], v[24:25], v[18:19]
	global_load_dwordx4 v[18:21], v[80:81], off offset:2048
	s_waitcnt vmcnt(0)
	v_pk_add_f32 v[20:21], v[22:23], v[20:21]
	v_pk_add_f32 v[18:19], v[24:25], v[18:19]
	v_cvt_pk_bf16_f32 v82, v20, v21
	v_add_co_u32_e32 v20, vcc, s13, v16
	v_cvt_pk_bf16_f32 v18, v18, v19
	s_nop 0
	v_addc_co_u32_e32 v21, vcc, 0, v17, vcc
	v_lshlrev_b32_e32 v75, 16, v18
	v_and_b32_e32 v77, 0xffff0000, v18
	global_load_dwordx4 v[16:19], v[20:21], off
	v_cmp_lt_i32_e32 vcc, v101, v100
	v_lshlrev_b32_e32 v89, 16, v82
	v_and_b32_e32 v87, 0xffff0000, v82
	v_cndmask_b32_e32 v73, v98, v101, vcc
	v_cmp_lt_i32_e32 vcc, v102, v100
	v_lshlrev_b32_e32 v73, 2, v73
	s_waitcnt vmcnt(0)
	v_pk_add_f32 v[22:23], v[18:19], 0 op_sel_hi:[1,0]
	v_pk_add_f32 v[24:25], v[16:17], 0 op_sel_hi:[1,0]
	global_load_dwordx4 v[16:19], v[2:3], off
	v_cndmask_b32_e32 v92, v98, v102, vcc
	v_cmp_lt_i32_e32 vcc, v103, v100
	v_lshlrev_b32_e32 v109, 2, v92
	s_waitcnt vmcnt(0)
	v_pk_add_f32 v[22:23], v[22:23], v[18:19]
	v_pk_add_f32 v[24:25], v[24:25], v[16:17]
	global_load_dwordx4 v[16:19], v[8:9], off
	v_cndmask_b32_e32 v92, v98, v103, vcc
	v_cmp_lt_i32_e32 vcc, v104, v100
	v_lshlrev_b32_e32 v108, 2, v92
	s_waitcnt vmcnt(0)
	v_pk_add_f32 v[22:23], v[22:23], v[18:19]
	v_pk_add_f32 v[24:25], v[24:25], v[16:17]
	global_load_dwordx4 v[16:19], v[12:13], off
	v_cndmask_b32_e32 v92, v98, v104, vcc
	v_lshlrev_b32_e32 v107, 2, v92
	v_cmp_lt_i32_e32 vcc, v105, v100
	s_waitcnt vmcnt(0)
	v_pk_add_f32 v[22:23], v[22:23], v[18:19]
	v_pk_add_f32 v[24:25], v[24:25], v[16:17]
	global_load_dwordx4 v[16:19], v[14:15], off
	s_waitcnt vmcnt(0)
	v_pk_add_f32 v[22:23], v[22:23], v[18:19]
	v_pk_add_f32 v[24:25], v[24:25], v[16:17]
	global_load_dwordx4 v[16:19], v[4:5], off
	s_waitcnt vmcnt(0)
	v_pk_add_f32 v[22:23], v[22:23], v[18:19]
	v_pk_add_f32 v[24:25], v[24:25], v[16:17]
	global_load_dwordx4 v[16:19], v[6:7], off
	s_waitcnt vmcnt(0)
	v_pk_add_f32 v[22:23], v[22:23], v[18:19]
	v_pk_add_f32 v[24:25], v[24:25], v[16:17]
	global_load_dwordx4 v[16:19], v[10:11], off
	s_waitcnt vmcnt(0)
	v_pk_add_f32 v[16:17], v[24:25], v[16:17]
	v_pk_add_f32 v[18:19], v[22:23], v[18:19]
	v_cvt_pk_bf16_f32 v16, v16, v17
	v_cvt_pk_bf16_f32 v84, v18, v19
	v_lshlrev_b32_e32 v80, 16, v16
	v_and_b32_e32 v78, 0xffff0000, v16
	global_load_dwordx4 v[16:19], v[20:21], off offset:2048
	v_lshlrev_b32_e32 v82, 16, v84
	v_and_b32_e32 v84, 0xffff0000, v84
	s_waitcnt vmcnt(0)
	v_pk_add_f32 v[20:21], v[18:19], 0 op_sel_hi:[1,0]
	v_pk_add_f32 v[22:23], v[16:17], 0 op_sel_hi:[1,0]
	global_load_dwordx4 v[16:19], v[2:3], off offset:2048
	s_waitcnt vmcnt(0)
	v_pk_add_f32 v[2:3], v[20:21], v[18:19]
	v_pk_add_f32 v[20:21], v[22:23], v[16:17]
	global_load_dwordx4 v[16:19], v[8:9], off offset:2048
	s_waitcnt vmcnt(0)
	v_pk_add_f32 v[2:3], v[2:3], v[18:19]
	v_pk_add_f32 v[8:9], v[20:21], v[16:17]
	global_load_dwordx4 v[16:19], v[12:13], off offset:2048
	s_waitcnt vmcnt(0)
	v_pk_add_f32 v[2:3], v[2:3], v[18:19]
	global_load_dwordx4 v[12:15], v[14:15], off offset:2048
	v_pk_add_f32 v[8:9], v[8:9], v[16:17]
	s_waitcnt vmcnt(0)
	v_pk_add_f32 v[14:15], v[2:3], v[14:15]
	global_load_dwordx4 v[2:5], v[4:5], off offset:2048
	v_pk_add_f32 v[8:9], v[8:9], v[12:13]
	s_waitcnt vmcnt(0)
	v_pk_add_f32 v[12:13], v[14:15], v[4:5]
	v_pk_add_f32 v[8:9], v[8:9], v[2:3]
	global_load_dwordx4 v[2:5], v[6:7], off offset:2048
	s_waitcnt vmcnt(0)
	v_pk_add_f32 v[6:7], v[12:13], v[4:5]
	v_pk_add_f32 v[8:9], v[8:9], v[2:3]
	global_load_dwordx4 v[2:5], v[10:11], off offset:2048
	s_waitcnt vmcnt(0)
	v_pk_add_f32 v[2:3], v[8:9], v[2:3]
	s_nop 0
	v_cvt_pk_bf16_f32 v2, v2, v3
	v_lshlrev_b32_e32 v79, 16, v2
	v_and_b32_e32 v81, 0xffff0000, v2
	v_lshl_add_u64 v[2:3], v[90:91], 0, v[38:39]
	global_load_dwordx4 v[30:33], v[2:3], off
	v_lshl_add_u64 v[2:3], v[90:91], 0, v[40:41]
	global_load_dwordx4 v[26:29], v[2:3], off
	v_lshl_add_u64 v[2:3], v[90:91], 0, v[42:43]
	global_load_dwordx4 v[22:25], v[2:3], off
	v_lshl_add_u64 v[2:3], v[90:91], 0, v[44:45]
	global_load_dwordx4 v[18:21], v[2:3], off
	v_lshl_add_u64 v[2:3], v[90:91], 0, v[46:47]
	global_load_dwordx4 v[14:17], v[2:3], off
	v_lshl_add_u64 v[2:3], v[90:91], 0, v[48:49]
	global_load_dwordx4 v[10:13], v[2:3], off
	v_lshl_add_u64 v[2:3], v[90:91], 0, v[50:51]
	v_pk_add_f32 v[4:5], v[6:7], v[4:5]
	global_load_dwordx4 v[6:9], v[2:3], off
	v_lshl_add_u64 v[2:3], v[90:91], 0, v[52:53]
	v_cvt_pk_bf16_f32 v85, v4, v5
	global_load_dwordx4 v[2:5], v[2:3], off
	v_lshlrev_b32_e32 v83, 16, v85
	v_and_b32_e32 v85, 0xffff0000, v85
	s_waitcnt vmcnt(7)
	v_pk_mul_f32 v[92:93], v[30:31], v[76:77]
	s_nop 0
	v_pk_fma_f32 v[92:93], v[30:31], v[74:75], v[92:93] op_sel:[1,0,0] op_sel_hi:[0,1,1]
	v_pk_fma_f32 v[92:93], v[32:33], v[88:89], v[92:93] op_sel_hi:[0,1,1]
	v_mov_b32_e32 v94, v33
	v_pk_fma_f32 v[92:93], v[94:95], v[86:87], v[92:93] op_sel_hi:[0,1,1]
	ds_bpermute_b32 v110, v73, v92
	ds_bpermute_b32 v111, v73, v93
	s_waitcnt lgkmcnt(0)
	v_pk_add_f32 v[92:93], v[92:93], v[110:111]
	ds_bpermute_b32 v110, v109, v92
	ds_bpermute_b32 v111, v109, v93
	s_waitcnt lgkmcnt(0)
	v_pk_add_f32 v[92:93], v[92:93], v[110:111]
	ds_bpermute_b32 v110, v108, v92
	ds_bpermute_b32 v111, v108, v93
	s_waitcnt lgkmcnt(0)
	v_pk_add_f32 v[92:93], v[92:93], v[110:111]
	ds_bpermute_b32 v110, v107, v92
	ds_bpermute_b32 v111, v107, v93
	s_waitcnt lgkmcnt(0)
	v_pk_add_f32 v[92:93], v[92:93], v[110:111]
	v_pk_mul_f32 v[110:111], v[30:31], v[80:81]
	s_nop 0
	v_pk_fma_f32 v[30:31], v[30:31], v[78:79], v[110:111] op_sel:[1,0,0] op_sel_hi:[0,1,1]
	v_pk_fma_f32 v[30:31], v[32:33], v[82:83], v[30:31] op_sel_hi:[0,1,1]
	v_pk_fma_f32 v[30:31], v[94:95], v[84:85], v[30:31] op_sel_hi:[0,1,1]
	ds_bpermute_b32 v32, v73, v30
	ds_bpermute_b32 v33, v73, v31
	s_waitcnt lgkmcnt(0)
	v_pk_add_f32 v[30:31], v[30:31], v[32:33]
	ds_bpermute_b32 v32, v109, v30
	ds_bpermute_b32 v33, v109, v31
	s_waitcnt lgkmcnt(0)
	v_pk_add_f32 v[30:31], v[30:31], v[32:33]
	ds_bpermute_b32 v32, v108, v30
	ds_bpermute_b32 v33, v108, v31
	s_waitcnt lgkmcnt(0)
	v_pk_add_f32 v[30:31], v[30:31], v[32:33]
	ds_bpermute_b32 v32, v107, v30
	ds_bpermute_b32 v33, v107, v31
	s_waitcnt lgkmcnt(0)
	v_pk_add_f32 v[30:31], v[30:31], v[32:33]
	v_cndmask_b32_e32 v32, v98, v105, vcc
	v_lshlrev_b32_e32 v110, 2, v32
	ds_bpermute_b32 v94, v110, v92
	ds_bpermute_b32 v95, v110, v93
	ds_bpermute_b32 v32, v110, v30
	ds_bpermute_b32 v33, v110, v31
	s_and_saveexec_b64 s[48:49], s[6:7]
	s_cbranch_execz .LBB0_1274
	s_waitcnt lgkmcnt(2)
	v_pk_add_f32 v[92:93], v[92:93], v[94:95]
	s_waitcnt lgkmcnt(0)
	v_pk_add_f32 v[30:31], v[30:31], v[32:33]
	s_nop 0
	v_pk_mul_f32 v[32:33], v[30:31], s[10:11] op_sel_hi:[1,0]
	v_pk_mul_f32 v[30:31], v[92:93], s[10:11] op_sel_hi:[1,0]
	ds_write_b128 v106, v[30:33]

.LBB0_3864:
	s_mov_b64 s[10:11], s[0:1]
	s_load_dwordx2 s[48:49], s[10:11], 0x10
	s_and_b32 s10, s9, -4
	s_and_b32 s66, s3, 0x180
	s_ashr_i32 s11, s10, 31
	s_lshl_b32 s12, s66, 2
	v_lshl_add_u64 v[2:3], v[36:37], 0, s[12:13]
	s_lshl_b64 vcc, s[10:11], 11
	s_mov_b64 s[46:47], s[0:1]
	v_lshl_add_u64 v[16:17], v[2:3], 0, vcc
	global_load_dwordx4 v[2:5], v[16:17], off offset:2048
	s_mov_b32 vcc_lo, 0x1000
	s_mov_b32 vcc_hi, 0
	s_nop 0
	v_lshl_add_u64 v[18:19], v[16:17], 0, vcc
	global_load_dwordx4 v[2:5], v[18:19], off
	global_load_dwordx4 v[2:5], v[18:19], off offset:2048
	s_mov_b32 vcc_lo, 0x40000
	s_mov_b32 vcc_hi, 0
	s_nop 0
	v_lshl_add_u64 v[18:19], v[16:17], 0, vcc
	global_load_dwordx4 v[2:5], v[18:19], off
	global_load_dwordx4 v[2:5], v[18:19], off offset:2048
	s_mov_b32 vcc_lo, 0x41000
	s_mov_b32 vcc_hi, 0
	s_nop 0
	v_lshl_add_u64 v[18:19], v[16:17], 0, vcc
	global_load_dwordx4 v[2:5], v[18:19], off
	global_load_dwordx4 v[2:5], v[18:19], off offset:2048
	s_mov_b32 vcc_lo, 0x80000
	s_mov_b32 vcc_hi, 0
	s_nop 0
	v_lshl_add_u64 v[18:19], v[16:17], 0, vcc
	global_load_dwordx4 v[2:5], v[18:19], off
	global_load_dwordx4 v[2:5], v[18:19], off offset:2048
	s_mov_b32 vcc_lo, 0x81000
	s_mov_b32 vcc_hi, 0
	s_nop 0
	v_lshl_add_u64 v[18:19], v[16:17], 0, vcc
	global_load_dwordx4 v[2:5], v[18:19], off
	global_load_dwordx4 v[2:5], v[18:19], off offset:2048
	s_mov_b32 vcc_lo, 0xc0000
	s_mov_b32 vcc_hi, 0
	s_nop 0
	v_lshl_add_u64 v[18:19], v[16:17], 0, vcc
	global_load_dwordx4 v[2:5], v[18:19], off
	global_load_dwordx4 v[2:5], v[18:19], off offset:2048
	s_mov_b32 vcc_lo, 0xc1000
	s_mov_b32 vcc_hi, 0
	s_nop 0
	v_lshl_add_u64 v[18:19], v[16:17], 0, vcc
	global_load_dwordx4 v[2:5], v[18:19], off
	global_load_dwordx4 v[2:5], v[18:19], off offset:2048
	s_mov_b32 vcc_lo, 0x100000
	s_mov_b32 vcc_hi, 0
	s_nop 0
	v_lshl_add_u64 v[18:19], v[16:17], 0, vcc
	global_load_dwordx4 v[2:5], v[18:19], off
	global_load_dwordx4 v[2:5], v[18:19], off offset:2048
	s_mov_b32 vcc_lo, 0x101000
	s_mov_b32 vcc_hi, 0
	s_nop 0
	v_lshl_add_u64 v[18:19], v[16:17], 0, vcc
	global_load_dwordx4 v[2:5], v[18:19], off
	global_load_dwordx4 v[2:5], v[18:19], off offset:2048
	s_mov_b32 vcc_lo, 0x140000
	s_mov_b32 vcc_hi, 0
	s_nop 0
	v_lshl_add_u64 v[18:19], v[16:17], 0, vcc
	global_load_dwordx4 v[2:5], v[18:19], off
	global_load_dwordx4 v[2:5], v[18:19], off offset:2048
	s_mov_b32 vcc_lo, 0x141000
	s_mov_b32 vcc_hi, 0
	s_nop 0
	v_lshl_add_u64 v[18:19], v[16:17], 0, vcc
	global_load_dwordx4 v[2:5], v[18:19], off
	global_load_dwordx4 v[2:5], v[18:19], off offset:2048
	s_mov_b32 vcc_lo, 0x180000
	s_mov_b32 vcc_hi, 0
	s_nop 0
	v_lshl_add_u64 v[18:19], v[16:17], 0, vcc
	global_load_dwordx4 v[2:5], v[18:19], off
	global_load_dwordx4 v[2:5], v[18:19], off offset:2048
	s_mov_b32 vcc_lo, 0x181000
	s_mov_b32 vcc_hi, 0
	s_nop 0
	v_lshl_add_u64 v[18:19], v[16:17], 0, vcc
	global_load_dwordx4 v[2:5], v[18:19], off
	global_load_dwordx4 v[2:5], v[18:19], off offset:2048
	s_mov_b32 vcc_lo, 0x1c0000
	s_mov_b32 vcc_hi, 0
	s_nop 0
	v_lshl_add_u64 v[18:19], v[16:17], 0, vcc
	global_load_dwordx4 v[2:5], v[18:19], off
	global_load_dwordx4 v[2:5], v[18:19], off offset:2048
	s_mov_b32 vcc_lo, 0x1c1000
	s_mov_b32 vcc_hi, 0
	s_nop 0
	v_lshl_add_u64 v[18:19], v[16:17], 0, vcc
	global_load_dwordx4 v[2:5], v[18:19], off
	global_load_dwordx4 v[2:5], v[18:19], off offset:2048
	global_load_dwordx4 v[2:5], v[16:17], off
	s_mov_b32 s11, 0x40000
	v_add_co_u32_e32 v18, vcc, s11, v16
	s_mov_b32 s11, 0x41000
	s_nop 0
	v_addc_co_u32_e32 v19, vcc, 0, v17, vcc
	s_ashr_i32 s50, s9, 2
	s_ashr_i32 s51, s50, 31
	s_lshl_b64 s[50:51], s[50:51], 17
	s_or_b32 s50, s50, s66
	s_lshl_b64 s[50:51], s[50:51], 2
	s_waitcnt lgkmcnt(0)
	s_add_u32 s48, s48, s50
	s_addc_u32 s49, s49, s51
	s_waitcnt vmcnt(0)
	v_pk_add_f32 v[10:11], v[2:3], 0 op_sel_hi:[1,0]
	v_add_co_u32_e32 v2, vcc, s11, v16
	v_pk_add_f32 v[8:9], v[4:5], 0 op_sel_hi:[1,0]
	s_nop 0
	v_addc_co_u32_e32 v3, vcc, 0, v17, vcc
	global_load_dwordx4 v[4:7], v[2:3], off offset:-4096
	s_mov_b32 s11, 0x80000
	v_add_co_u32_e32 v20, vcc, s11, v16
	s_mov_b32 s11, 0x81000
	s_nop 0
	v_addc_co_u32_e32 v21, vcc, 0, v17, vcc
	s_waitcnt vmcnt(0)
	v_pk_add_f32 v[12:13], v[8:9], v[6:7]
	v_add_co_u32_e32 v6, vcc, s11, v16
	v_pk_add_f32 v[4:5], v[10:11], v[4:5]
	s_nop 0
	v_addc_co_u32_e32 v7, vcc, 0, v17, vcc
	global_load_dwordx4 v[8:11], v[6:7], off offset:-4096
	s_mov_b32 s11, 0xc0000
	v_add_co_u32_e32 v26, vcc, s11, v16
	s_mov_b32 s11, 0xc1000
	s_nop 0
	v_addc_co_u32_e32 v27, vcc, 0, v17, vcc
	s_waitcnt vmcnt(0)
	v_pk_add_f32 v[14:15], v[12:13], v[10:11]
	v_add_co_u32_e32 v12, vcc, s11, v16
	v_pk_add_f32 v[4:5], v[4:5], v[8:9]
	s_nop 0
	v_addc_co_u32_e32 v13, vcc, 0, v17, vcc
	global_load_dwordx4 v[8:11], v[12:13], off offset:-4096
	s_mov_b32 s11, 0x100000
	v_add_co_u32_e32 v28, vcc, s11, v16
	s_mov_b32 s11, 0x101000
	s_nop 0
	v_addc_co_u32_e32 v29, vcc, 0, v17, vcc
	s_waitcnt vmcnt(0)
	v_pk_add_f32 v[22:23], v[14:15], v[10:11]
	v_add_co_u32_e32 v14, vcc, s11, v16
	v_pk_add_f32 v[4:5], v[4:5], v[8:9]
	s_nop 0
	v_addc_co_u32_e32 v15, vcc, 0, v17, vcc
	global_load_dwordx4 v[8:11], v[14:15], off offset:-4096
	s_mov_b32 s11, 0x140000
	v_add_co_u32_e32 v30, vcc, s11, v16
	s_mov_b32 s11, 0x141000
	s_nop 0
	v_addc_co_u32_e32 v31, vcc, 0, v17, vcc
	s_waitcnt vmcnt(0)
	v_pk_add_f32 v[4:5], v[4:5], v[8:9]
	v_add_co_u32_e32 v8, vcc, s11, v16
	v_pk_add_f32 v[10:11], v[22:23], v[10:11]
	s_nop 0
	v_addc_co_u32_e32 v9, vcc, 0, v17, vcc
	global_load_dwordx4 v[22:25], v[8:9], off offset:-4096
	s_mov_b32 s11, 0x180000
	v_add_co_u32_e32 v78, vcc, s11, v16
	s_mov_b32 s11, 0x181000
	s_nop 0
	v_addc_co_u32_e32 v79, vcc, 0, v17, vcc
	s_waitcnt vmcnt(0)
	v_pk_add_f32 v[32:33], v[4:5], v[22:23]
	v_add_co_u32_e32 v4, vcc, s11, v16
	v_pk_add_f32 v[10:11], v[10:11], v[24:25]
	s_nop 0
	v_addc_co_u32_e32 v5, vcc, 0, v17, vcc
	global_load_dwordx4 v[22:25], v[4:5], off offset:-4096
	s_mov_b32 s11, 0x1c0000
	v_add_co_u32_e32 v80, vcc, s11, v16
	s_mov_b32 s11, 0x1c1000
	s_nop 0
	v_addc_co_u32_e32 v81, vcc, 0, v17, vcc
	s_waitcnt vmcnt(0)
	v_pk_add_f32 v[74:75], v[10:11], v[24:25]
	v_add_co_u32_e32 v10, vcc, s11, v16
	v_pk_add_f32 v[32:33], v[32:33], v[22:23]
	s_nop 0
	v_addc_co_u32_e32 v11, vcc, 0, v17, vcc
	global_load_dwordx4 v[22:25], v[10:11], off offset:-4096
	s_movk_i32 s11, 0x1000
	s_waitcnt vmcnt(0)
	v_pk_add_f32 v[22:23], v[32:33], v[22:23]
	v_pk_add_f32 v[24:25], v[74:75], v[24:25]
	v_cvt_pk_bf16_f32 v22, v22, v23
	v_cvt_pk_bf16_f32 v73, v24, v25
	v_lshlrev_b32_e32 v76, 16, v22
	v_and_b32_e32 v74, 0xffff0000, v22
	global_load_dwordx4 v[22:25], v[16:17], off offset:2048
	v_lshlrev_b32_e32 v88, 16, v73
	v_and_b32_e32 v86, 0xffff0000, v73
	s_waitcnt vmcnt(0)
	v_pk_add_f32 v[32:33], v[24:25], 0 op_sel_hi:[1,0]
	v_pk_add_f32 v[82:83], v[22:23], 0 op_sel_hi:[1,0]
	global_load_dwordx4 v[22:25], v[18:19], off offset:2048
	s_waitcnt vmcnt(0)
	v_pk_add_f32 v[24:25], v[32:33], v[24:25]
	global_load_dwordx4 v[18:21], v[20:21], off offset:2048
	v_pk_add_f32 v[22:23], v[82:83], v[22:23]
	s_waitcnt vmcnt(0)
	v_pk_add_f32 v[24:25], v[24:25], v[20:21]
	v_pk_add_f32 v[22:23], v[22:23], v[18:19]
	global_load_dwordx4 v[18:21], v[26:27], off offset:2048
	s_waitcnt vmcnt(0)
	v_pk_add_f32 v[24:25], v[24:25], v[20:21]
	v_pk_add_f32 v[22:23], v[22:23], v[18:19]
	global_load_dwordx4 v[18:21], v[28:29], off offset:2048
	s_waitcnt vmcnt(0)
	v_pk_add_f32 v[24:25], v[24:25], v[20:21]
	v_pk_add_f32 v[22:23], v[22:23], v[18:19]
	global_load_dwordx4 v[18:21], v[30:31], off offset:2048
	s_waitcnt vmcnt(0)
	v_pk_add_f32 v[24:25], v[24:25], v[20:21]
	v_pk_add_f32 v[22:23], v[22:23], v[18:19]
	global_load_dwordx4 v[18:21], v[78:79], off offset:2048
	s_waitcnt vmcnt(0)
	v_pk_add_f32 v[24:25], v[24:25], v[20:21]
	v_pk_add_f32 v[22:23], v[22:23], v[18:19]
	global_load_dwordx4 v[18:21], v[80:81], off offset:2048
	s_waitcnt vmcnt(0)
	v_pk_add_f32 v[20:21], v[24:25], v[20:21]
	v_pk_add_f32 v[18:19], v[22:23], v[18:19]
	v_cvt_pk_bf16_f32 v82, v20, v21
	v_add_co_u32_e32 v20, vcc, s11, v16
	v_cvt_pk_bf16_f32 v18, v18, v19
	s_nop 0
	v_addc_co_u32_e32 v21, vcc, 0, v17, vcc
	v_lshlrev_b32_e32 v75, 16, v18
	v_and_b32_e32 v77, 0xffff0000, v18
	global_load_dwordx4 v[16:19], v[20:21], off
	v_cmp_lt_i32_e32 vcc, v102, v101
	v_lshlrev_b32_e32 v89, 16, v82
	v_and_b32_e32 v87, 0xffff0000, v82
	v_cndmask_b32_e32 v73, v99, v102, vcc
	v_cmp_lt_i32_e32 vcc, v103, v101
	v_lshlrev_b32_e32 v73, 2, v73
	s_waitcnt vmcnt(0)
	v_pk_add_f32 v[22:23], v[18:19], 0 op_sel_hi:[1,0]
	v_pk_add_f32 v[24:25], v[16:17], 0 op_sel_hi:[1,0]
	global_load_dwordx4 v[16:19], v[2:3], off
	v_cndmask_b32_e32 v92, v99, v103, vcc
	v_cmp_lt_i32_e32 vcc, v104, v101
	v_lshlrev_b32_e32 v110, 2, v92
	s_waitcnt vmcnt(0)
	v_pk_add_f32 v[22:23], v[22:23], v[18:19]
	v_pk_add_f32 v[24:25], v[24:25], v[16:17]
	global_load_dwordx4 v[16:19], v[6:7], off
	v_cndmask_b32_e32 v92, v99, v104, vcc
	v_cmp_lt_i32_e32 vcc, v105, v101
	v_lshlrev_b32_e32 v109, 2, v92
	s_waitcnt vmcnt(0)
	v_pk_add_f32 v[22:23], v[22:23], v[18:19]
	v_pk_add_f32 v[24:25], v[24:25], v[16:17]
	global_load_dwordx4 v[16:19], v[12:13], off
	v_cndmask_b32_e32 v92, v99, v105, vcc
	v_lshlrev_b32_e32 v108, 2, v92
	v_cmp_lt_i32_e32 vcc, v106, v101
	s_waitcnt vmcnt(0)
	v_pk_add_f32 v[22:23], v[22:23], v[18:19]
	v_pk_add_f32 v[24:25], v[24:25], v[16:17]
	global_load_dwordx4 v[16:19], v[14:15], off
	s_waitcnt vmcnt(0)
	v_pk_add_f32 v[22:23], v[22:23], v[18:19]
	v_pk_add_f32 v[24:25], v[24:25], v[16:17]
	global_load_dwordx4 v[16:19], v[8:9], off
	s_waitcnt vmcnt(0)
	v_pk_add_f32 v[22:23], v[22:23], v[18:19]
	v_pk_add_f32 v[24:25], v[24:25], v[16:17]
	global_load_dwordx4 v[16:19], v[4:5], off
	s_waitcnt vmcnt(0)
	v_pk_add_f32 v[22:23], v[22:23], v[18:19]
	v_pk_add_f32 v[24:25], v[24:25], v[16:17]
	global_load_dwordx4 v[16:19], v[10:11], off
	s_waitcnt vmcnt(0)
	v_pk_add_f32 v[16:17], v[24:25], v[16:17]
	v_pk_add_f32 v[18:19], v[22:23], v[18:19]
	v_cvt_pk_bf16_f32 v16, v16, v17
	v_cvt_pk_bf16_f32 v84, v18, v19
	v_lshlrev_b32_e32 v80, 16, v16
	v_and_b32_e32 v78, 0xffff0000, v16
	global_load_dwordx4 v[16:19], v[20:21], off offset:2048
	v_lshlrev_b32_e32 v82, 16, v84
	v_and_b32_e32 v84, 0xffff0000, v84
	s_waitcnt vmcnt(0)
	v_pk_add_f32 v[20:21], v[18:19], 0 op_sel_hi:[1,0]
	v_pk_add_f32 v[22:23], v[16:17], 0 op_sel_hi:[1,0]
	global_load_dwordx4 v[16:19], v[2:3], off offset:2048
	s_waitcnt vmcnt(0)
	v_pk_add_f32 v[2:3], v[20:21], v[18:19]
	v_pk_add_f32 v[20:21], v[22:23], v[16:17]
	global_load_dwordx4 v[16:19], v[6:7], off offset:2048
	s_waitcnt vmcnt(0)
	v_pk_add_f32 v[2:3], v[2:3], v[18:19]
	v_pk_add_f32 v[6:7], v[20:21], v[16:17]
	global_load_dwordx4 v[16:19], v[12:13], off offset:2048
	s_waitcnt vmcnt(0)
	v_pk_add_f32 v[6:7], v[6:7], v[16:17]
	global_load_dwordx4 v[12:15], v[14:15], off offset:2048
	v_pk_add_f32 v[2:3], v[2:3], v[18:19]
	s_waitcnt vmcnt(0)
	v_pk_add_f32 v[12:13], v[6:7], v[12:13]
	global_load_dwordx4 v[6:9], v[8:9], off offset:2048
	v_pk_add_f32 v[2:3], v[2:3], v[14:15]
	s_waitcnt vmcnt(0)
	v_pk_add_f32 v[6:7], v[12:13], v[6:7]
	v_pk_add_f32 v[8:9], v[2:3], v[8:9]
	global_load_dwordx4 v[2:5], v[4:5], off offset:2048
	s_waitcnt vmcnt(0)
	v_pk_add_f32 v[8:9], v[8:9], v[4:5]
	v_pk_add_f32 v[6:7], v[6:7], v[2:3]
	global_load_dwordx4 v[2:5], v[10:11], off offset:2048
	s_waitcnt vmcnt(0)
	v_pk_add_f32 v[2:3], v[6:7], v[2:3]
	s_nop 0
	v_cvt_pk_bf16_f32 v2, v2, v3
	v_lshlrev_b32_e32 v79, 16, v2
	v_and_b32_e32 v81, 0xffff0000, v2
	v_lshl_add_u64 v[2:3], s[48:49], 0, v[70:71]
	v_lshl_add_u64 v[90:91], v[2:3], 0, s[40:41]
	v_lshl_add_u64 v[2:3], v[90:91], 0, v[38:39]
	global_load_dwordx4 v[30:33], v[2:3], off
	v_lshl_add_u64 v[2:3], v[90:91], 0, v[40:41]
	global_load_dwordx4 v[26:29], v[2:3], off
	v_lshl_add_u64 v[2:3], v[90:91], 0, v[42:43]
	global_load_dwordx4 v[22:25], v[2:3], off
	v_lshl_add_u64 v[2:3], v[90:91], 0, v[44:45]
	global_load_dwordx4 v[18:21], v[2:3], off
	v_lshl_add_u64 v[2:3], v[90:91], 0, v[46:47]
	global_load_dwordx4 v[14:17], v[2:3], off
	v_lshl_add_u64 v[2:3], v[90:91], 0, v[48:49]
	global_load_dwordx4 v[10:13], v[2:3], off
	v_lshl_add_u64 v[2:3], v[90:91], 0, v[50:51]
	v_pk_add_f32 v[4:5], v[8:9], v[4:5]
	global_load_dwordx4 v[6:9], v[2:3], off
	v_lshl_add_u64 v[2:3], v[90:91], 0, v[52:53]
	v_cvt_pk_bf16_f32 v85, v4, v5
	global_load_dwordx4 v[2:5], v[2:3], off
	v_lshlrev_b32_e32 v83, 16, v85
	v_and_b32_e32 v85, 0xffff0000, v85
	s_waitcnt vmcnt(7)
	v_pk_mul_f32 v[92:93], v[30:31], v[76:77]
	s_nop 0
	v_pk_fma_f32 v[92:93], v[30:31], v[74:75], v[92:93] op_sel:[1,0,0] op_sel_hi:[0,1,1]
	v_pk_fma_f32 v[92:93], v[32:33], v[88:89], v[92:93] op_sel_hi:[0,1,1]
	v_mov_b32_e32 v94, v33
	v_pk_fma_f32 v[92:93], v[94:95], v[86:87], v[92:93] op_sel_hi:[0,1,1]
	ds_bpermute_b32 v112, v73, v92
	ds_bpermute_b32 v113, v73, v93
	s_waitcnt lgkmcnt(0)
	v_pk_add_f32 v[92:93], v[92:93], v[112:113]
	ds_bpermute_b32 v112, v110, v92
	ds_bpermute_b32 v113, v110, v93
	s_waitcnt lgkmcnt(0)
	v_pk_add_f32 v[92:93], v[92:93], v[112:113]
	ds_bpermute_b32 v112, v109, v92
	ds_bpermute_b32 v113, v109, v93
	s_waitcnt lgkmcnt(0)
	v_pk_add_f32 v[92:93], v[92:93], v[112:113]
	ds_bpermute_b32 v112, v108, v92
	ds_bpermute_b32 v113, v108, v93
	s_waitcnt lgkmcnt(0)
	v_pk_add_f32 v[92:93], v[92:93], v[112:113]
	v_pk_mul_f32 v[112:113], v[30:31], v[80:81]
	s_nop 0
	v_pk_fma_f32 v[30:31], v[30:31], v[78:79], v[112:113] op_sel:[1,0,0] op_sel_hi:[0,1,1]
	v_pk_fma_f32 v[30:31], v[32:33], v[82:83], v[30:31] op_sel_hi:[0,1,1]
	v_pk_fma_f32 v[30:31], v[94:95], v[84:85], v[30:31] op_sel_hi:[0,1,1]
	ds_bpermute_b32 v32, v73, v30
	ds_bpermute_b32 v33, v73, v31
	s_waitcnt lgkmcnt(0)
	v_pk_add_f32 v[30:31], v[30:31], v[32:33]
	ds_bpermute_b32 v32, v110, v30
	ds_bpermute_b32 v33, v110, v31
	s_waitcnt lgkmcnt(0)
	v_pk_add_f32 v[30:31], v[30:31], v[32:33]
	ds_bpermute_b32 v32, v109, v30
	ds_bpermute_b32 v33, v109, v31
	s_waitcnt lgkmcnt(0)
	v_pk_add_f32 v[30:31], v[30:31], v[32:33]
	ds_bpermute_b32 v32, v108, v30
	ds_bpermute_b32 v33, v108, v31
	s_waitcnt lgkmcnt(0)
	v_pk_add_f32 v[30:31], v[30:31], v[32:33]
	v_cndmask_b32_e32 v32, v99, v106, vcc
	v_lshlrev_b32_e32 v111, 2, v32
	ds_bpermute_b32 v94, v111, v92
	ds_bpermute_b32 v95, v111, v93
	ds_bpermute_b32 v32, v111, v30
	ds_bpermute_b32 v33, v111, v31
	s_and_saveexec_b64 s[48:49], s[4:5]
	s_cbranch_execz .LBB0_3866
	s_waitcnt lgkmcnt(2)
	v_pk_add_f32 v[92:93], v[92:93], v[94:95]
	s_waitcnt lgkmcnt(0)
	v_pk_add_f32 v[30:31], v[30:31], v[32:33]
	s_nop 0
	v_pk_mul_f32 v[32:33], v[30:31], s[8:9] op_sel_hi:[1,0]
	v_pk_mul_f32 v[30:31], v[92:93], s[8:9] op_sel_hi:[1,0]
	ds_write_b128 v107, v[30:33]
